# stack3 with the vcc write->v_cndmask wait states restored at the end of the rewritten attention epilogue (no functional change)
# speedup vs baseline: 1.0002x; 1.0002x over previous
; #define SBAR() __builtin_amdgcn_sched_barrier(0)
; __device__ __forceinline__ int crow(int r, int hi) { return (r & 3) + 8 * (r >> 2) + 4 * hi; }
; #define SEAM_K0() do { VMWN(NQL); if constexpr (F32) { SWRITE_KF(0); SBAR(); SLOAD_F((const float*)nxt.V, kbn); } else { SWRITE_HK(0); } SBAR(); } while (0)
; template <class TIn, class TOut>
; __device__ __forceinline__ void causal_swa_block(const BlockRef<TIn, TOut>& cur, const BlockRef<TIn, TOut>& nxt, int skv, int W, char* lds, Seam<TIn>& S) {
;     ...
;     SBAR(); SEAM_K0();
;     S.mk = m_reg; S.lk = l_reg;
;     if (hi == 0) li_l[r32] = l_reg; asm volatile("s_waitcnt lgkmcnt(0)" ::: "memory");
;     float rli[16];
; #pragma unroll
;     for (int r = 0; r < 16; ++r) rli[r] = __builtin_amdgcn_rcpf(li_l[crow(r, hi)]);
;     TOut* Ow = cur.O + (size_t)(wid * QBLK) * LD;
; #pragma unroll
;     for (int r = 0; r < 16; ++r) { const int orow = crow(r, hi);
; #pragma unroll
;         for (int d0 = 0; d0 < 4; ++d0) { const float v = o[d0][r] * rli[r];
;             if constexpr (same_t<TOut, float>::v) { Ow[(size_t)orow * LD + d0 * 32 + r32] = v; }
;             else { const float vn = __shfl_xor(v, 1);
;                    if ((r32 & 1) == 0) *(unsigned*)(Ow + (unsigned)(orow * LD + d0 * 32 + r32)) = cvtpk(v, vn); } } }
.LBB0_551:
	s_waitcnt vmcnt(8)
	s_waitcnt vmcnt(9)
	ds_write_b128 v227, v[120:123] offset:32768
	s_waitcnt vmcnt(8)
	ds_write_b128 v227, v[124:127] offset:40960
	s_and_saveexec_b64 s[34:35], s[40:41]
	ds_write_b32 v226, v220
	s_or_b64 exec, exec, s[34:35]
	s_waitcnt lgkmcnt(0)
	v_add_u32_e32 v64, s83, v224
	ds_read_b128 v[76:79], v64
	ds_read_b128 v[72:75], v64 offset:32
	v_cmp_lt_i32_e32 vcc, v213, v212
	v_and_b32_e32 v82, 1, v221
	ds_read_b128 v[68:71], v64 offset:64
	ds_read_b128 v[64:67], v64 offset:96
	s_waitcnt lgkmcnt(0)
	v_and_b32_e32 v82, 1, v221
	v_cmp_eq_u32_e64 s[40:41], 0, v82
	v_cmp_eq_u32_e32 vcc, 1, v82
	s_ashr_i32 s83, s82, 31
	s_lshl_b64 s[34:35], s[82:83], 12
	s_add_u32 s42, s74, s34
	s_addc_u32 s43, s75, s35
	s_lshl_b32 s34, s82, 8
	s_add_i32 s34, s34, 0x10800
	s_cmp_lt_u32 s82, 0xe0
	s_cselect_b32 s34, s34, 0x21000
	v_lshl_add_u32 v83, v223, 2, v82
	v_lshrrev_b32_e32 v81, 1, v222
	v_lshlrev_b32_e32 v81, 2, v81
	v_lshl_add_u32 v83, v83, 8, v81
	v_add_u32_e32 v83, s34, v83
	v_rcp_f32_e32 v76, v76
	v_rcp_f32_e32 v77, v77
	v_rcp_f32_e32 v78, v78
	v_rcp_f32_e32 v79, v79
	v_mul_f32_e32 v32, v32, v76
	v_mul_f32_e32 v33, v33, v77
	v_mul_f32_e32 v34, v34, v78
	v_mul_f32_e32 v35, v35, v79
	v_mul_f32_e32 v48, v48, v76
	v_mul_f32_e32 v49, v49, v77
	v_mul_f32_e32 v50, v50, v78
	v_mul_f32_e32 v51, v51, v79
	v_mul_f32_e32 v16, v16, v76
	v_mul_f32_e32 v17, v17, v77
	v_mul_f32_e32 v18, v18, v78
	v_mul_f32_e32 v19, v19, v79
	v_mul_f32_e32 v0, v0, v76
	v_mul_f32_e32 v1, v1, v77
	v_mul_f32_e32 v2, v2, v78
	v_mul_f32_e32 v3, v3, v79
	v_and_b32_e32 v78, 63, v221
	v_lshlrev_b32_e32 v76, 4, v78
	v_add_u32_e32 v76, s34, v76
	v_lshrrev_b32_e32 v79, 4, v78
	v_and_b32_e32 v78, 15, v78
	v_lshlrev_b32_e32 v78, 4, v78
	v_lshl_add_u32 v77, v79, 12, v78
	v_mov_b32_dpp v81, v32 quad_perm:[1,0,3,2] row_mask:0xf bank_mask:0xf
	v_mov_b32_dpp v128, v33 quad_perm:[1,0,3,2] row_mask:0xf bank_mask:0xf
	v_cndmask_b32_e32 v32, v32, v128, vcc
	v_cndmask_b32_e32 v33, v81, v33, vcc
	v_cvt_pk_bf16_f32 v32, v32, v33
	ds_write_b32 v83, v32 offset:0
	v_mov_b32_dpp v81, v34 quad_perm:[1,0,3,2] row_mask:0xf bank_mask:0xf
	v_mov_b32_dpp v128, v35 quad_perm:[1,0,3,2] row_mask:0xf bank_mask:0xf
	v_cndmask_b32_e32 v34, v34, v128, vcc
	v_cndmask_b32_e32 v35, v81, v35, vcc
	v_cvt_pk_bf16_f32 v34, v34, v35
	ds_write_b32 v83, v34 offset:512
	v_mov_b32_dpp v81, v48 quad_perm:[1,0,3,2] row_mask:0xf bank_mask:0xf
	v_mov_b32_dpp v128, v49 quad_perm:[1,0,3,2] row_mask:0xf bank_mask:0xf
	v_cndmask_b32_e32 v48, v48, v128, vcc
	v_cndmask_b32_e32 v49, v81, v49, vcc
	v_cvt_pk_bf16_f32 v48, v48, v49
	ds_write_b32 v83, v48 offset:64
	v_mov_b32_dpp v81, v50 quad_perm:[1,0,3,2] row_mask:0xf bank_mask:0xf
	v_mov_b32_dpp v128, v51 quad_perm:[1,0,3,2] row_mask:0xf bank_mask:0xf
	v_cndmask_b32_e32 v50, v50, v128, vcc
	v_cndmask_b32_e32 v51, v81, v51, vcc
	v_cvt_pk_bf16_f32 v50, v50, v51
	ds_write_b32 v83, v50 offset:576
	v_mov_b32_dpp v81, v16 quad_perm:[1,0,3,2] row_mask:0xf bank_mask:0xf
	v_mov_b32_dpp v128, v17 quad_perm:[1,0,3,2] row_mask:0xf bank_mask:0xf
	v_cndmask_b32_e32 v16, v16, v128, vcc
	v_cndmask_b32_e32 v17, v81, v17, vcc
	v_cvt_pk_bf16_f32 v16, v16, v17
	ds_write_b32 v83, v16 offset:128
	v_mov_b32_dpp v81, v18 quad_perm:[1,0,3,2] row_mask:0xf bank_mask:0xf
	v_mov_b32_dpp v128, v19 quad_perm:[1,0,3,2] row_mask:0xf bank_mask:0xf
	v_cndmask_b32_e32 v18, v18, v128, vcc
	v_cndmask_b32_e32 v19, v81, v19, vcc
	v_cvt_pk_bf16_f32 v18, v18, v19
	ds_write_b32 v83, v18 offset:640
	v_mov_b32_dpp v81, v0 quad_perm:[1,0,3,2] row_mask:0xf bank_mask:0xf
	v_mov_b32_dpp v128, v1 quad_perm:[1,0,3,2] row_mask:0xf bank_mask:0xf
	v_cndmask_b32_e32 v0, v0, v128, vcc
	v_cndmask_b32_e32 v1, v81, v1, vcc
	v_cvt_pk_bf16_f32 v0, v0, v1
	ds_write_b32 v83, v0 offset:192
	v_mov_b32_dpp v81, v2 quad_perm:[1,0,3,2] row_mask:0xf bank_mask:0xf
	v_mov_b32_dpp v128, v3 quad_perm:[1,0,3,2] row_mask:0xf bank_mask:0xf
	v_cndmask_b32_e32 v2, v2, v128, vcc
	v_cndmask_b32_e32 v3, v81, v3, vcc
	v_cvt_pk_bf16_f32 v2, v2, v3
	ds_write_b32 v83, v2 offset:704
	ds_read_b128 v[32:35], v76 offset:0
	ds_read_b128 v[48:51], v76 offset:1024
	v_rcp_f32_e32 v72, v72
	v_rcp_f32_e32 v73, v73
	v_rcp_f32_e32 v74, v74
	v_rcp_f32_e32 v75, v75
	v_mul_f32_e32 v36, v36, v72
	v_mul_f32_e32 v37, v37, v73
	v_mul_f32_e32 v38, v38, v74
	v_mul_f32_e32 v39, v39, v75
	v_mul_f32_e32 v52, v52, v72
	v_mul_f32_e32 v53, v53, v73
	v_mul_f32_e32 v54, v54, v74
	v_mul_f32_e32 v55, v55, v75
	v_mul_f32_e32 v20, v20, v72
	v_mul_f32_e32 v21, v21, v73
	v_mul_f32_e32 v22, v22, v74
	v_mul_f32_e32 v23, v23, v75
	v_mul_f32_e32 v4, v4, v72
	v_mul_f32_e32 v5, v5, v73
	v_mul_f32_e32 v6, v6, v74
	v_mul_f32_e32 v7, v7, v75
	v_mov_b32_dpp v81, v36 quad_perm:[1,0,3,2] row_mask:0xf bank_mask:0xf
	v_mov_b32_dpp v128, v37 quad_perm:[1,0,3,2] row_mask:0xf bank_mask:0xf
	v_cndmask_b32_e32 v36, v36, v128, vcc
	v_cndmask_b32_e32 v37, v81, v37, vcc
	v_cvt_pk_bf16_f32 v36, v36, v37
	ds_write_b32 v83, v36 offset:2048
	v_mov_b32_dpp v81, v38 quad_perm:[1,0,3,2] row_mask:0xf bank_mask:0xf
	v_mov_b32_dpp v128, v39 quad_perm:[1,0,3,2] row_mask:0xf bank_mask:0xf
	v_cndmask_b32_e32 v38, v38, v128, vcc
	v_cndmask_b32_e32 v39, v81, v39, vcc
	v_cvt_pk_bf16_f32 v38, v38, v39
	ds_write_b32 v83, v38 offset:2560
	v_mov_b32_dpp v81, v52 quad_perm:[1,0,3,2] row_mask:0xf bank_mask:0xf
	v_mov_b32_dpp v128, v53 quad_perm:[1,0,3,2] row_mask:0xf bank_mask:0xf
	v_cndmask_b32_e32 v52, v52, v128, vcc
	v_cndmask_b32_e32 v53, v81, v53, vcc
	v_cvt_pk_bf16_f32 v52, v52, v53
	ds_write_b32 v83, v52 offset:2112
	v_mov_b32_dpp v81, v54 quad_perm:[1,0,3,2] row_mask:0xf bank_mask:0xf
	v_mov_b32_dpp v128, v55 quad_perm:[1,0,3,2] row_mask:0xf bank_mask:0xf
	v_cndmask_b32_e32 v54, v54, v128, vcc
	v_cndmask_b32_e32 v55, v81, v55, vcc
	v_cvt_pk_bf16_f32 v54, v54, v55
	ds_write_b32 v83, v54 offset:2624
	v_mov_b32_dpp v81, v20 quad_perm:[1,0,3,2] row_mask:0xf bank_mask:0xf
	v_mov_b32_dpp v128, v21 quad_perm:[1,0,3,2] row_mask:0xf bank_mask:0xf
	v_cndmask_b32_e32 v20, v20, v128, vcc
	v_cndmask_b32_e32 v21, v81, v21, vcc
	v_cvt_pk_bf16_f32 v20, v20, v21
	ds_write_b32 v83, v20 offset:2176
	v_mov_b32_dpp v81, v22 quad_perm:[1,0,3,2] row_mask:0xf bank_mask:0xf
	v_mov_b32_dpp v128, v23 quad_perm:[1,0,3,2] row_mask:0xf bank_mask:0xf
	v_cndmask_b32_e32 v22, v22, v128, vcc
	v_cndmask_b32_e32 v23, v81, v23, vcc
	v_cvt_pk_bf16_f32 v22, v22, v23
	ds_write_b32 v83, v22 offset:2688
	v_mov_b32_dpp v81, v4 quad_perm:[1,0,3,2] row_mask:0xf bank_mask:0xf
	v_mov_b32_dpp v128, v5 quad_perm:[1,0,3,2] row_mask:0xf bank_mask:0xf
	v_cndmask_b32_e32 v4, v4, v128, vcc
	v_cndmask_b32_e32 v5, v81, v5, vcc
	v_cvt_pk_bf16_f32 v4, v4, v5
	ds_write_b32 v83, v4 offset:2240
	v_mov_b32_dpp v81, v6 quad_perm:[1,0,3,2] row_mask:0xf bank_mask:0xf
	v_mov_b32_dpp v128, v7 quad_perm:[1,0,3,2] row_mask:0xf bank_mask:0xf
	v_cndmask_b32_e32 v6, v6, v128, vcc
	v_cndmask_b32_e32 v7, v81, v7, vcc
	v_cvt_pk_bf16_f32 v6, v6, v7
	ds_write_b32 v83, v6 offset:2752
	s_waitcnt lgkmcnt(8)
; __device__ __forceinline__ int crow(int r, int hi) { return (r & 3) + 8 * (r >> 2) + 4 * hi; }
; template <class TIn, class TOut>
; __device__ __forceinline__ void causal_swa_block(const BlockRef<TIn, TOut>& cur, const BlockRef<TIn, TOut>& nxt, int skv, int W, char* lds, Seam<TIn>& S) {
;     ...
;     const int j_lo = swa_jlo(cur.P0, W);
;     int j_hi = (cur.P0 + QB - 1) / KVBLK + 1; if (j_hi > skv / KVBLK) j_hi = skv / KVBLK;
;     const int NT = j_hi - j_lo;
;     ...
;     for (int r = 0; r < 16; ++r) { const int orow = crow(r, hi);
; #pragma unroll
;         for (int d0 = 0; d0 < 4; ++d0) { const float v = o[d0][r] * rli[r];
;             if constexpr (same_t<TOut, float>::v) { Ow[(size_t)orow * LD + d0 * 32 + r32] = v; }
;             else { const float vn = __shfl_xor(v, 1);
;                    if ((r32 & 1) == 0) *(unsigned*)(Ow + (unsigned)(orow * LD + d0 * 32 + r32)) = cvtpk(v, vn); } } }
	global_store_dwordx4 v77, v[32:35], s[42:43]
	s_add_u32 s42, s42, 0x4000
	s_addc_u32 s43, s43, 0
	global_store_dwordx4 v77, v[48:51], s[42:43]
	s_add_u32 s42, s42, 0x4000
	s_addc_u32 s43, s43, 0
	ds_read_b128 v[36:39], v76 offset:2048
	ds_read_b128 v[52:55], v76 offset:3072
	v_rcp_f32_e32 v68, v68
	v_rcp_f32_e32 v69, v69
	v_rcp_f32_e32 v70, v70
	v_rcp_f32_e32 v71, v71
	v_mul_f32_e32 v40, v40, v68
	v_mul_f32_e32 v41, v41, v69
	v_mul_f32_e32 v42, v42, v70
	v_mul_f32_e32 v43, v43, v71
	v_mul_f32_e32 v56, v56, v68
	v_mul_f32_e32 v57, v57, v69
	v_mul_f32_e32 v58, v58, v70
	v_mul_f32_e32 v59, v59, v71
	v_mul_f32_e32 v24, v24, v68
	v_mul_f32_e32 v25, v25, v69
	v_mul_f32_e32 v26, v26, v70
	v_mul_f32_e32 v27, v27, v71
	v_mul_f32_e32 v8, v8, v68
	v_mul_f32_e32 v9, v9, v69
	v_mul_f32_e32 v10, v10, v70
	v_mul_f32_e32 v11, v11, v71
	v_mov_b32_dpp v81, v40 quad_perm:[1,0,3,2] row_mask:0xf bank_mask:0xf
	v_mov_b32_dpp v128, v41 quad_perm:[1,0,3,2] row_mask:0xf bank_mask:0xf
	v_cndmask_b32_e32 v40, v40, v128, vcc
	v_cndmask_b32_e32 v41, v81, v41, vcc
	v_cvt_pk_bf16_f32 v40, v40, v41
	ds_write_b32 v83, v40 offset:4096
	v_mov_b32_dpp v81, v42 quad_perm:[1,0,3,2] row_mask:0xf bank_mask:0xf
	v_mov_b32_dpp v128, v43 quad_perm:[1,0,3,2] row_mask:0xf bank_mask:0xf
	v_cndmask_b32_e32 v42, v42, v128, vcc
	v_cndmask_b32_e32 v43, v81, v43, vcc
	v_cvt_pk_bf16_f32 v42, v42, v43
	ds_write_b32 v83, v42 offset:4608
	v_mov_b32_dpp v81, v56 quad_perm:[1,0,3,2] row_mask:0xf bank_mask:0xf
	v_mov_b32_dpp v128, v57 quad_perm:[1,0,3,2] row_mask:0xf bank_mask:0xf
	v_cndmask_b32_e32 v56, v56, v128, vcc
	v_cndmask_b32_e32 v57, v81, v57, vcc
	v_cvt_pk_bf16_f32 v56, v56, v57
	ds_write_b32 v83, v56 offset:4160
	v_mov_b32_dpp v81, v58 quad_perm:[1,0,3,2] row_mask:0xf bank_mask:0xf
	v_mov_b32_dpp v128, v59 quad_perm:[1,0,3,2] row_mask:0xf bank_mask:0xf
	v_cndmask_b32_e32 v58, v58, v128, vcc
	v_cndmask_b32_e32 v59, v81, v59, vcc
	v_cvt_pk_bf16_f32 v58, v58, v59
	ds_write_b32 v83, v58 offset:4672
	v_mov_b32_dpp v81, v24 quad_perm:[1,0,3,2] row_mask:0xf bank_mask:0xf
	v_mov_b32_dpp v128, v25 quad_perm:[1,0,3,2] row_mask:0xf bank_mask:0xf
	v_cndmask_b32_e32 v24, v24, v128, vcc
	v_cndmask_b32_e32 v25, v81, v25, vcc
	v_cvt_pk_bf16_f32 v24, v24, v25
	ds_write_b32 v83, v24 offset:4224
	v_mov_b32_dpp v81, v26 quad_perm:[1,0,3,2] row_mask:0xf bank_mask:0xf
	v_mov_b32_dpp v128, v27 quad_perm:[1,0,3,2] row_mask:0xf bank_mask:0xf
	v_cndmask_b32_e32 v26, v26, v128, vcc
	v_cndmask_b32_e32 v27, v81, v27, vcc
	v_cvt_pk_bf16_f32 v26, v26, v27
	ds_write_b32 v83, v26 offset:4736
	v_mov_b32_dpp v81, v8 quad_perm:[1,0,3,2] row_mask:0xf bank_mask:0xf
	v_mov_b32_dpp v128, v9 quad_perm:[1,0,3,2] row_mask:0xf bank_mask:0xf
	v_cndmask_b32_e32 v8, v8, v128, vcc
	v_cndmask_b32_e32 v9, v81, v9, vcc
	v_cvt_pk_bf16_f32 v8, v8, v9
	ds_write_b32 v83, v8 offset:4288
	v_mov_b32_dpp v81, v10 quad_perm:[1,0,3,2] row_mask:0xf bank_mask:0xf
	v_mov_b32_dpp v128, v11 quad_perm:[1,0,3,2] row_mask:0xf bank_mask:0xf
	v_cndmask_b32_e32 v10, v10, v128, vcc
	v_cndmask_b32_e32 v11, v81, v11, vcc
	v_cvt_pk_bf16_f32 v10, v10, v11
	ds_write_b32 v83, v10 offset:4800
	s_waitcnt lgkmcnt(8)
	global_store_dwordx4 v77, v[36:39], s[42:43]
	s_add_u32 s42, s42, 0x4000
	s_addc_u32 s43, s43, 0
	global_store_dwordx4 v77, v[52:55], s[42:43]
	s_add_u32 s42, s42, 0x4000
	s_addc_u32 s43, s43, 0
	ds_read_b128 v[40:43], v76 offset:4096
	ds_read_b128 v[56:59], v76 offset:5120
	v_rcp_f32_e32 v64, v64
	v_rcp_f32_e32 v65, v65
	v_rcp_f32_e32 v66, v66
	v_rcp_f32_e32 v67, v67
	v_mul_f32_e32 v44, v44, v64
	v_mul_f32_e32 v45, v45, v65
	v_mul_f32_e32 v46, v46, v66
	v_mul_f32_e32 v47, v47, v67
	v_mul_f32_e32 v60, v60, v64
	v_mul_f32_e32 v61, v61, v65
	v_mul_f32_e32 v62, v62, v66
	v_mul_f32_e32 v63, v63, v67
	v_mul_f32_e32 v28, v28, v64
	v_mul_f32_e32 v29, v29, v65
	v_mul_f32_e32 v30, v30, v66
	v_mul_f32_e32 v31, v31, v67
	v_mul_f32_e32 v12, v12, v64
	v_mul_f32_e32 v13, v13, v65
	v_mul_f32_e32 v14, v14, v66
	v_mul_f32_e32 v15, v15, v67
	v_mov_b32_dpp v81, v44 quad_perm:[1,0,3,2] row_mask:0xf bank_mask:0xf
	v_mov_b32_dpp v128, v45 quad_perm:[1,0,3,2] row_mask:0xf bank_mask:0xf
	v_cndmask_b32_e32 v44, v44, v128, vcc
	v_cndmask_b32_e32 v45, v81, v45, vcc
	v_cvt_pk_bf16_f32 v44, v44, v45
	ds_write_b32 v83, v44 offset:6144
	v_mov_b32_dpp v81, v46 quad_perm:[1,0,3,2] row_mask:0xf bank_mask:0xf
	v_mov_b32_dpp v128, v47 quad_perm:[1,0,3,2] row_mask:0xf bank_mask:0xf
	v_cndmask_b32_e32 v46, v46, v128, vcc
	v_cndmask_b32_e32 v47, v81, v47, vcc
	v_cvt_pk_bf16_f32 v46, v46, v47
	ds_write_b32 v83, v46 offset:6656
	v_mov_b32_dpp v81, v60 quad_perm:[1,0,3,2] row_mask:0xf bank_mask:0xf
	v_mov_b32_dpp v128, v61 quad_perm:[1,0,3,2] row_mask:0xf bank_mask:0xf
	v_cndmask_b32_e32 v60, v60, v128, vcc
	v_cndmask_b32_e32 v61, v81, v61, vcc
	v_cvt_pk_bf16_f32 v60, v60, v61
	ds_write_b32 v83, v60 offset:6208
	v_mov_b32_dpp v81, v62 quad_perm:[1,0,3,2] row_mask:0xf bank_mask:0xf
	v_mov_b32_dpp v128, v63 quad_perm:[1,0,3,2] row_mask:0xf bank_mask:0xf
	v_cndmask_b32_e32 v62, v62, v128, vcc
	v_cndmask_b32_e32 v63, v81, v63, vcc
	v_cvt_pk_bf16_f32 v62, v62, v63
	ds_write_b32 v83, v62 offset:6720
	v_mov_b32_dpp v81, v28 quad_perm:[1,0,3,2] row_mask:0xf bank_mask:0xf
	v_mov_b32_dpp v128, v29 quad_perm:[1,0,3,2] row_mask:0xf bank_mask:0xf
	v_cndmask_b32_e32 v28, v28, v128, vcc
	v_cndmask_b32_e32 v29, v81, v29, vcc
	v_cvt_pk_bf16_f32 v28, v28, v29
	ds_write_b32 v83, v28 offset:6272
	v_mov_b32_dpp v81, v30 quad_perm:[1,0,3,2] row_mask:0xf bank_mask:0xf
	v_mov_b32_dpp v128, v31 quad_perm:[1,0,3,2] row_mask:0xf bank_mask:0xf
	v_cndmask_b32_e32 v30, v30, v128, vcc
	v_cndmask_b32_e32 v31, v81, v31, vcc
	v_cvt_pk_bf16_f32 v30, v30, v31
	ds_write_b32 v83, v30 offset:6784
	v_mov_b32_dpp v81, v12 quad_perm:[1,0,3,2] row_mask:0xf bank_mask:0xf
	v_mov_b32_dpp v128, v13 quad_perm:[1,0,3,2] row_mask:0xf bank_mask:0xf
	v_cndmask_b32_e32 v12, v12, v128, vcc
	v_cndmask_b32_e32 v13, v81, v13, vcc
	v_cvt_pk_bf16_f32 v12, v12, v13
	ds_write_b32 v83, v12 offset:6336
	v_mov_b32_dpp v81, v14 quad_perm:[1,0,3,2] row_mask:0xf bank_mask:0xf
	v_mov_b32_dpp v128, v15 quad_perm:[1,0,3,2] row_mask:0xf bank_mask:0xf
	v_cndmask_b32_e32 v14, v14, v128, vcc
	v_cndmask_b32_e32 v15, v81, v15, vcc
	v_cvt_pk_bf16_f32 v14, v14, v15
	ds_write_b32 v83, v14 offset:6848
	s_waitcnt lgkmcnt(8)
	global_store_dwordx4 v77, v[40:43], s[42:43]
	s_add_u32 s42, s42, 0x4000
	s_addc_u32 s43, s43, 0
	global_store_dwordx4 v77, v[56:59], s[42:43]
	s_add_u32 s42, s42, 0x4000
	s_addc_u32 s43, s43, 0
	ds_read_b128 v[44:47], v76 offset:6144
	ds_read_b128 v[60:63], v76 offset:7168
	s_waitcnt lgkmcnt(0)
	global_store_dwordx4 v77, v[44:47], s[42:43]
	s_add_u32 s42, s42, 0x4000
	s_addc_u32 s43, s43, 0
	global_store_dwordx4 v77, v[60:63], s[42:43]
	v_cmp_lt_i32_e32 vcc, v213, v212
	v_lshl_or_b32 v83, v223, 13, v222
	v_lshlrev_b32_e32 v128, 1, v83
	s_nop 0
	v_cndmask_b32_e32 v76, v211, v213, vcc
	v_lshlrev_b32_e32 v76, 2, v76
	s_branch .LBB0_498
